# workgroup-local barrier after the gate GEMM without the L1 invalidate (own writes only)
# speedup vs baseline: 1.0058x; 1.0036x over previous
.Lpb_local:
	s_waitcnt vmcnt(0)
	s_mov_b64 s[4:5], exec
	s_branch .LBB0_22
